# cache-policy tuning: nt (streaming) hint on the w_in GEMM epilogue stores, on top of v40
# speedup vs baseline: 1.0048x; 1.0048x over previous
.LBB0_567:
	s_cmp_lt_i32 s2, 4
	s_cbranch_scc1 .LBB0_603
	s_cmp_lg_u32 s2, 4
	s_cbranch_scc0 .LBB0_600
	s_cmp_gt_u32 s2, 6
	s_cbranch_scc0 .LBB0_597
	s_cmp_gt_u32 s2, 8
	s_cbranch_scc0 .LBB0_578
	s_cmp_gt_u32 s2, 16
	s_cbranch_scc0 .LBB0_575
	s_andn2_b64 vcc, exec, s[18:19]
	s_cbranch_vccnz .LBB0_574
	v_lshlrev_b64 v[128:129], 7, v[210:211]
	v_lshl_add_u64 v[140:141], v[184:185], 0, v[128:129]
	v_pk_mul_f32 v[130:131], v[126:127], v[214:215] op_sel_hi:[1,0]
	v_pk_mul_f32 v[128:129], v[124:125], v[214:215] op_sel_hi:[1,0]
	v_mul_f32_e32 v130, 0xbfb8aa3b, v130
	v_mul_f32_e32 v128, 0xbfb8aa3b, v128
	v_mul_f32_e32 v129, 0xbfb8aa3b, v129
	v_mul_f32_e32 v131, 0xbfb8aa3b, v131
	v_exp_f32_e32 v128, v128
	v_exp_f32_e32 v129, v129
	v_exp_f32_e32 v130, v130
	v_exp_f32_e32 v131, v131
	v_add_f32_e32 v128, 1.0, v128
	v_add_f32_e32 v129, 1.0, v129
	v_add_f32_e32 v130, 1.0, v130
	v_add_f32_e32 v131, 1.0, v131
	v_rcp_f32_e32 v128, v128
	v_rcp_f32_e32 v129, v129
	v_rcp_f32_e32 v130, v130
	v_rcp_f32_e32 v131, v131
	global_store_dwordx4 v[140:141], v[128:131], off nt
	s_nop 1
	v_pk_mul_f32 v[130:131], v[118:119], v[214:215] op_sel_hi:[1,0]
	v_pk_mul_f32 v[128:129], v[116:117], v[214:215] op_sel_hi:[1,0]
	v_mul_f32_e32 v130, 0xbfb8aa3b, v130
	v_mul_f32_e32 v128, 0xbfb8aa3b, v128
	v_mul_f32_e32 v129, 0xbfb8aa3b, v129
	v_mul_f32_e32 v131, 0xbfb8aa3b, v131
	v_exp_f32_e32 v128, v128
	v_exp_f32_e32 v129, v129
	v_exp_f32_e32 v130, v130
	v_exp_f32_e32 v131, v131
	v_add_f32_e32 v128, 1.0, v128
	v_add_f32_e32 v129, 1.0, v129
	v_add_f32_e32 v130, 1.0, v130
	v_add_f32_e32 v131, 1.0, v131
	v_rcp_f32_e32 v128, v128
	v_rcp_f32_e32 v129, v129
	v_rcp_f32_e32 v130, v130
	v_rcp_f32_e32 v131, v131
	global_store_dwordx4 v[140:141], v[128:131], off offset:16 nt
	s_nop 1
	v_lshlrev_b64 v[128:129], 7, v[208:209]
	v_lshl_add_u64 v[140:141], v[184:185], 0, v[128:129]
	v_pk_mul_f32 v[130:131], v[110:111], v[212:213] op_sel_hi:[1,0]
	v_pk_mul_f32 v[128:129], v[108:109], v[212:213] op_sel_hi:[1,0]
	v_mul_f32_e32 v130, 0xbfb8aa3b, v130
	v_mul_f32_e32 v128, 0xbfb8aa3b, v128
	v_mul_f32_e32 v129, 0xbfb8aa3b, v129
	v_mul_f32_e32 v131, 0xbfb8aa3b, v131
	v_exp_f32_e32 v128, v128
	v_exp_f32_e32 v129, v129
	v_exp_f32_e32 v130, v130
	v_exp_f32_e32 v131, v131
	v_add_f32_e32 v128, 1.0, v128
	v_add_f32_e32 v129, 1.0, v129
	v_add_f32_e32 v130, 1.0, v130
	v_add_f32_e32 v131, 1.0, v131
	v_rcp_f32_e32 v128, v128
	v_rcp_f32_e32 v129, v129
	v_rcp_f32_e32 v130, v130
	v_rcp_f32_e32 v131, v131
	global_store_dwordx4 v[140:141], v[128:131], off nt
	s_nop 1
	v_pk_mul_f32 v[130:131], v[102:103], v[212:213] op_sel_hi:[1,0]
	v_pk_mul_f32 v[128:129], v[100:101], v[212:213] op_sel_hi:[1,0]
	v_mul_f32_e32 v130, 0xbfb8aa3b, v130
	v_mul_f32_e32 v128, 0xbfb8aa3b, v128
	v_mul_f32_e32 v129, 0xbfb8aa3b, v129
	v_mul_f32_e32 v131, 0xbfb8aa3b, v131
	v_exp_f32_e32 v128, v128
	v_exp_f32_e32 v129, v129
	v_exp_f32_e32 v130, v130
	v_exp_f32_e32 v131, v131
	v_add_f32_e32 v128, 1.0, v128
	v_add_f32_e32 v129, 1.0, v129
	v_add_f32_e32 v130, 1.0, v130
	v_add_f32_e32 v131, 1.0, v131
	v_rcp_f32_e32 v128, v128
	v_rcp_f32_e32 v129, v129
	v_rcp_f32_e32 v130, v130
	v_rcp_f32_e32 v131, v131
	global_store_dwordx4 v[140:141], v[128:131], off offset:16 nt
	s_nop 1
	v_lshlrev_b64 v[128:129], 7, v[206:207]
	v_lshl_add_u64 v[140:141], v[184:185], 0, v[128:129]
	v_pk_mul_f32 v[130:131], v[94:95], v[146:147] op_sel_hi:[1,0]
	v_pk_mul_f32 v[128:129], v[92:93], v[146:147] op_sel_hi:[1,0]
	v_mul_f32_e32 v130, 0xbfb8aa3b, v130
	v_mul_f32_e32 v128, 0xbfb8aa3b, v128
	v_mul_f32_e32 v129, 0xbfb8aa3b, v129
	v_mul_f32_e32 v131, 0xbfb8aa3b, v131
	v_exp_f32_e32 v128, v128
	v_exp_f32_e32 v129, v129
	v_exp_f32_e32 v130, v130
	v_exp_f32_e32 v131, v131
	v_add_f32_e32 v128, 1.0, v128
	v_add_f32_e32 v129, 1.0, v129
	v_add_f32_e32 v130, 1.0, v130
	v_add_f32_e32 v131, 1.0, v131
	v_rcp_f32_e32 v128, v128
	v_rcp_f32_e32 v129, v129
	v_rcp_f32_e32 v130, v130
	v_rcp_f32_e32 v131, v131
	global_store_dwordx4 v[140:141], v[128:131], off nt
	s_nop 1
	v_pk_mul_f32 v[130:131], v[86:87], v[146:147] op_sel_hi:[1,0]
	v_pk_mul_f32 v[128:129], v[84:85], v[146:147] op_sel_hi:[1,0]
	v_mul_f32_e32 v130, 0xbfb8aa3b, v130
	v_mul_f32_e32 v128, 0xbfb8aa3b, v128
	v_mul_f32_e32 v129, 0xbfb8aa3b, v129
	v_mul_f32_e32 v131, 0xbfb8aa3b, v131
	v_exp_f32_e32 v128, v128
	v_exp_f32_e32 v129, v129
	v_exp_f32_e32 v130, v130
	v_exp_f32_e32 v131, v131
	v_add_f32_e32 v128, 1.0, v128
	v_add_f32_e32 v129, 1.0, v129
	v_add_f32_e32 v130, 1.0, v130
	v_add_f32_e32 v131, 1.0, v131
	v_rcp_f32_e32 v128, v128
	v_rcp_f32_e32 v129, v129
	v_rcp_f32_e32 v130, v130
	v_rcp_f32_e32 v131, v131
	global_store_dwordx4 v[140:141], v[128:131], off offset:16 nt
	s_nop 1
	v_lshlrev_b64 v[128:129], 7, v[204:205]
	v_lshl_add_u64 v[140:141], v[184:185], 0, v[128:129]
	v_pk_mul_f32 v[130:131], v[78:79], v[144:145] op_sel_hi:[1,0]
	v_pk_mul_f32 v[128:129], v[76:77], v[144:145] op_sel_hi:[1,0]
	v_mul_f32_e32 v130, 0xbfb8aa3b, v130
	v_mul_f32_e32 v128, 0xbfb8aa3b, v128
	v_mul_f32_e32 v129, 0xbfb8aa3b, v129
	v_mul_f32_e32 v131, 0xbfb8aa3b, v131
	v_exp_f32_e32 v128, v128
	v_exp_f32_e32 v129, v129
	v_exp_f32_e32 v130, v130
	v_exp_f32_e32 v131, v131
	v_add_f32_e32 v128, 1.0, v128
	v_add_f32_e32 v129, 1.0, v129
	v_add_f32_e32 v130, 1.0, v130
	v_add_f32_e32 v131, 1.0, v131
	v_rcp_f32_e32 v128, v128
	v_rcp_f32_e32 v129, v129
	v_rcp_f32_e32 v130, v130
	v_rcp_f32_e32 v131, v131
	global_store_dwordx4 v[140:141], v[128:131], off nt
	s_nop 1
	v_pk_mul_f32 v[130:131], v[70:71], v[144:145] op_sel_hi:[1,0]
	v_pk_mul_f32 v[128:129], v[68:69], v[144:145] op_sel_hi:[1,0]
	v_mul_f32_e32 v130, 0xbfb8aa3b, v130
	v_mul_f32_e32 v128, 0xbfb8aa3b, v128
	v_mul_f32_e32 v129, 0xbfb8aa3b, v129
	v_mul_f32_e32 v131, 0xbfb8aa3b, v131
	v_exp_f32_e32 v128, v128
	v_exp_f32_e32 v129, v129
	v_exp_f32_e32 v130, v130
	v_exp_f32_e32 v131, v131
	v_add_f32_e32 v128, 1.0, v128
	v_add_f32_e32 v129, 1.0, v129
	v_add_f32_e32 v130, 1.0, v130
	v_add_f32_e32 v131, 1.0, v131
	v_rcp_f32_e32 v128, v128
	v_rcp_f32_e32 v129, v129
	v_rcp_f32_e32 v130, v130
	v_rcp_f32_e32 v131, v131
	global_store_dwordx4 v[140:141], v[128:131], off offset:16 nt
	s_nop 1
	v_lshlrev_b64 v[128:129], 7, v[202:203]
	v_lshl_add_u64 v[140:141], v[184:185], 0, v[128:129]
	v_pk_mul_f32 v[130:131], v[62:63], v[138:139] op_sel_hi:[1,0]
	v_pk_mul_f32 v[128:129], v[60:61], v[138:139] op_sel_hi:[1,0]
	v_mul_f32_e32 v130, 0xbfb8aa3b, v130
	v_mul_f32_e32 v128, 0xbfb8aa3b, v128
	v_mul_f32_e32 v129, 0xbfb8aa3b, v129
	v_mul_f32_e32 v131, 0xbfb8aa3b, v131
	v_exp_f32_e32 v128, v128
	v_exp_f32_e32 v129, v129
	v_exp_f32_e32 v130, v130
	v_exp_f32_e32 v131, v131
	v_add_f32_e32 v128, 1.0, v128
	v_add_f32_e32 v129, 1.0, v129
	v_add_f32_e32 v130, 1.0, v130
	v_add_f32_e32 v131, 1.0, v131
	v_rcp_f32_e32 v128, v128
	v_rcp_f32_e32 v129, v129
	v_rcp_f32_e32 v130, v130
	v_rcp_f32_e32 v131, v131
	global_store_dwordx4 v[140:141], v[128:131], off nt
	s_nop 1
	v_pk_mul_f32 v[130:131], v[54:55], v[138:139] op_sel_hi:[1,0]
	v_pk_mul_f32 v[128:129], v[52:53], v[138:139] op_sel_hi:[1,0]
	v_mul_f32_e32 v130, 0xbfb8aa3b, v130
	v_mul_f32_e32 v128, 0xbfb8aa3b, v128
	v_mul_f32_e32 v129, 0xbfb8aa3b, v129
	v_mul_f32_e32 v131, 0xbfb8aa3b, v131
	v_exp_f32_e32 v128, v128
	v_exp_f32_e32 v129, v129
	v_exp_f32_e32 v130, v130
	v_exp_f32_e32 v131, v131
	v_add_f32_e32 v128, 1.0, v128
	v_add_f32_e32 v129, 1.0, v129
	v_add_f32_e32 v130, 1.0, v130
	v_add_f32_e32 v131, 1.0, v131
	v_rcp_f32_e32 v128, v128
	v_rcp_f32_e32 v129, v129
	v_rcp_f32_e32 v130, v130
	v_rcp_f32_e32 v131, v131
	global_store_dwordx4 v[140:141], v[128:131], off offset:16 nt
	s_nop 1
	v_lshlrev_b64 v[128:129], 7, v[200:201]
	v_lshl_add_u64 v[140:141], v[184:185], 0, v[128:129]
	v_pk_mul_f32 v[130:131], v[46:47], v[136:137] op_sel_hi:[1,0]
	v_pk_mul_f32 v[128:129], v[44:45], v[136:137] op_sel_hi:[1,0]
	v_mul_f32_e32 v130, 0xbfb8aa3b, v130
	v_mul_f32_e32 v128, 0xbfb8aa3b, v128
	v_mul_f32_e32 v129, 0xbfb8aa3b, v129
	v_mul_f32_e32 v131, 0xbfb8aa3b, v131
	v_exp_f32_e32 v128, v128
	v_exp_f32_e32 v129, v129
	v_exp_f32_e32 v130, v130
	v_exp_f32_e32 v131, v131
	v_add_f32_e32 v128, 1.0, v128
	v_add_f32_e32 v129, 1.0, v129
	v_add_f32_e32 v130, 1.0, v130
	v_add_f32_e32 v131, 1.0, v131
	v_rcp_f32_e32 v128, v128
	v_rcp_f32_e32 v129, v129
	v_rcp_f32_e32 v130, v130
	v_rcp_f32_e32 v131, v131
	global_store_dwordx4 v[140:141], v[128:131], off nt
	s_nop 1
	v_pk_mul_f32 v[130:131], v[38:39], v[136:137] op_sel_hi:[1,0]
	v_pk_mul_f32 v[128:129], v[36:37], v[136:137] op_sel_hi:[1,0]
	v_mul_f32_e32 v130, 0xbfb8aa3b, v130
	v_mul_f32_e32 v128, 0xbfb8aa3b, v128
	v_mul_f32_e32 v129, 0xbfb8aa3b, v129
	v_mul_f32_e32 v131, 0xbfb8aa3b, v131
	v_exp_f32_e32 v128, v128
	v_exp_f32_e32 v129, v129
	v_exp_f32_e32 v130, v130
	v_exp_f32_e32 v131, v131
	v_add_f32_e32 v128, 1.0, v128
	v_add_f32_e32 v129, 1.0, v129
	v_add_f32_e32 v130, 1.0, v130
	v_add_f32_e32 v131, 1.0, v131
	v_rcp_f32_e32 v128, v128
	v_rcp_f32_e32 v129, v129
	v_rcp_f32_e32 v130, v130
	v_rcp_f32_e32 v131, v131
	global_store_dwordx4 v[140:141], v[128:131], off offset:16 nt
	s_nop 1
	v_lshlrev_b64 v[128:129], 7, v[198:199]
	v_lshl_add_u64 v[140:141], v[184:185], 0, v[128:129]
	v_pk_mul_f32 v[130:131], v[30:31], v[134:135] op_sel_hi:[1,0]
	v_pk_mul_f32 v[128:129], v[28:29], v[134:135] op_sel_hi:[1,0]
	v_mul_f32_e32 v130, 0xbfb8aa3b, v130
	v_mul_f32_e32 v128, 0xbfb8aa3b, v128
	v_mul_f32_e32 v129, 0xbfb8aa3b, v129
	v_mul_f32_e32 v131, 0xbfb8aa3b, v131
	v_exp_f32_e32 v128, v128
	v_exp_f32_e32 v129, v129
	v_exp_f32_e32 v130, v130
	v_exp_f32_e32 v131, v131
	v_add_f32_e32 v128, 1.0, v128
	v_add_f32_e32 v129, 1.0, v129
	v_add_f32_e32 v130, 1.0, v130
	v_add_f32_e32 v131, 1.0, v131
	v_rcp_f32_e32 v128, v128
	v_rcp_f32_e32 v129, v129
	v_rcp_f32_e32 v130, v130
	v_rcp_f32_e32 v131, v131
	global_store_dwordx4 v[140:141], v[128:131], off nt
	s_nop 1
	v_pk_mul_f32 v[130:131], v[22:23], v[134:135] op_sel_hi:[1,0]
	v_pk_mul_f32 v[128:129], v[20:21], v[134:135] op_sel_hi:[1,0]
	v_mul_f32_e32 v130, 0xbfb8aa3b, v130
	v_mul_f32_e32 v128, 0xbfb8aa3b, v128
	v_mul_f32_e32 v129, 0xbfb8aa3b, v129
	v_mul_f32_e32 v131, 0xbfb8aa3b, v131
	v_exp_f32_e32 v128, v128
	v_exp_f32_e32 v129, v129
	v_exp_f32_e32 v130, v130
	v_exp_f32_e32 v131, v131
	v_add_f32_e32 v128, 1.0, v128
	v_add_f32_e32 v129, 1.0, v129
	v_add_f32_e32 v130, 1.0, v130
	v_add_f32_e32 v131, 1.0, v131
	v_rcp_f32_e32 v128, v128
	v_rcp_f32_e32 v129, v129
	v_rcp_f32_e32 v130, v130
	v_rcp_f32_e32 v131, v131
	global_store_dwordx4 v[140:141], v[128:131], off offset:16 nt
	s_nop 1
	v_lshlrev_b64 v[128:129], 7, v[196:197]
	v_lshl_add_u64 v[140:141], v[184:185], 0, v[128:129]
	v_pk_mul_f32 v[130:131], v[14:15], v[132:133] op_sel_hi:[1,0]
	v_pk_mul_f32 v[128:129], v[12:13], v[132:133] op_sel_hi:[1,0]
	v_mul_f32_e32 v130, 0xbfb8aa3b, v130
	v_mul_f32_e32 v128, 0xbfb8aa3b, v128
	v_mul_f32_e32 v129, 0xbfb8aa3b, v129
	v_mul_f32_e32 v131, 0xbfb8aa3b, v131
	v_exp_f32_e32 v128, v128
	v_exp_f32_e32 v129, v129
	v_exp_f32_e32 v130, v130
	v_exp_f32_e32 v131, v131
	v_add_f32_e32 v128, 1.0, v128
	v_add_f32_e32 v129, 1.0, v129
	v_add_f32_e32 v130, 1.0, v130
	v_add_f32_e32 v131, 1.0, v131
	v_rcp_f32_e32 v128, v128
	v_rcp_f32_e32 v129, v129
	v_rcp_f32_e32 v130, v130
	v_rcp_f32_e32 v131, v131
	global_store_dwordx4 v[140:141], v[128:131], off nt
	s_nop 1
	v_pk_mul_f32 v[130:131], v[6:7], v[132:133] op_sel_hi:[1,0]
	v_pk_mul_f32 v[128:129], v[4:5], v[132:133] op_sel_hi:[1,0]
	v_mul_f32_e32 v130, 0xbfb8aa3b, v130
	v_mul_f32_e32 v128, 0xbfb8aa3b, v128
	v_mul_f32_e32 v129, 0xbfb8aa3b, v129
	v_mul_f32_e32 v131, 0xbfb8aa3b, v131
	v_exp_f32_e32 v128, v128
	v_exp_f32_e32 v129, v129
	v_exp_f32_e32 v130, v130
	v_exp_f32_e32 v131, v131
	v_add_f32_e32 v128, 1.0, v128
	v_add_f32_e32 v129, 1.0, v129
	v_add_f32_e32 v130, 1.0, v130
	v_add_f32_e32 v131, 1.0, v131
	v_rcp_f32_e32 v128, v128
	v_rcp_f32_e32 v129, v129
	v_rcp_f32_e32 v130, v130
	v_rcp_f32_e32 v131, v131
	global_store_dwordx4 v[140:141], v[128:131], off offset:16 nt

.LBB0_575:
	s_andn2_b64 vcc, exec, s[0:1]
	s_cbranch_vccnz .LBB0_577
	v_pk_mul_f32 v[140:141], v[124:125], v[214:215] op_sel_hi:[1,0]
	s_lshl_b32 s0, s2, 9
	v_mul_f32_e32 v133, 0xbfb8aa3b, v140
	v_mul_f32_e32 v135, 0xbfb8aa3b, v141
	v_pk_mul_f32 v[140:141], v[126:127], v[214:215] op_sel_hi:[1,0]
	s_add_u32 s0, s4, s0
	v_mul_f32_e32 v137, 0xbfb8aa3b, v140
	v_mul_f32_e32 v139, 0xbfb8aa3b, v141
	v_pk_mul_f32 v[140:141], v[116:117], v[214:215] op_sel_hi:[1,0]
	v_exp_f32_e32 v133, v133
	v_mul_f32_e32 v140, 0xbfb8aa3b, v140
	v_exp_f32_e32 v142, v140
	v_mul_f32_e32 v140, 0xbfb8aa3b, v141
	v_exp_f32_e32 v143, v140
	v_pk_mul_f32 v[140:141], v[118:119], v[214:215] op_sel_hi:[1,0]
	v_exp_f32_e32 v135, v135
	v_mul_f32_e32 v140, 0xbfb8aa3b, v140
	v_exp_f32_e32 v140, v140
	v_mul_f32_e32 v141, 0xbfb8aa3b, v141
	v_exp_f32_e32 v137, v137
	v_exp_f32_e32 v139, v139
	v_exp_f32_e32 v141, v141
	s_addc_u32 s1, s5, 0
	s_cmp_lt_u32 s2, 13
	s_mov_b32 s23, 0x11ffee00
	s_cselect_b32 s23, s23, 0x15ffe600
	v_add_f32_e32 v140, 1.0, v140
	s_add_u32 s0, s0, s23
	v_add_f32_e32 v133, 1.0, v133
	v_add_f32_e32 v135, 1.0, v135
	v_add_f32_e32 v137, 1.0, v137
	v_add_f32_e32 v139, 1.0, v139
	v_add_f32_e32 v142, 1.0, v142
	v_add_f32_e32 v143, 1.0, v143
	v_rcp_f32_e32 v145, v140
	v_add_f32_e32 v140, 1.0, v141
	s_addc_u32 s1, s1, 0
	s_lshl_b32 s23, s51, 1
	v_rcp_f32_e32 v133, v133
	v_rcp_f32_e32 v135, v135
	v_rcp_f32_e32 v137, v137
	v_rcp_f32_e32 v139, v139
	v_rcp_f32_e32 v142, v142
	v_rcp_f32_e32 v143, v143
	v_rcp_f32_e32 v147, v140
	s_add_u32 s0, s0, s23
	s_addc_u32 s1, s1, 0
	v_lshlrev_b32_e32 v168, 1, v160
	v_lshl_add_u64 v[128:129], s[0:1], 0, v[168:169]
	v_lshlrev_b64 v[130:131], 11, v[210:211]
	v_lshl_add_u64 v[130:131], v[128:129], 0, v[130:131]
	v_cvt_pk_bf16_f32 v140, v133, v135
	v_cvt_pk_bf16_f32 v141, v137, v139
	v_cvt_pk_bf16_f32 v142, v142, v143
	v_cvt_pk_bf16_f32 v143, v145, v147
	global_store_dwordx4 v[130:131], v[140:143], off nt
	s_nop 1
	v_pk_mul_f32 v[140:141], v[120:121], v[214:215] op_sel_hi:[1,0]
	s_nop 0
	v_mul_f32_e32 v133, 0xbfb8aa3b, v140
	v_mul_f32_e32 v135, 0xbfb8aa3b, v141
	v_pk_mul_f32 v[140:141], v[122:123], v[214:215] op_sel_hi:[1,0]
	v_exp_f32_e32 v133, v133
	v_mul_f32_e32 v137, 0xbfb8aa3b, v140
	v_mul_f32_e32 v139, 0xbfb8aa3b, v141
	v_pk_mul_f32 v[140:141], v[112:113], v[214:215] op_sel_hi:[1,0]
	v_exp_f32_e32 v135, v135
	v_mul_f32_e32 v140, 0xbfb8aa3b, v140
	v_exp_f32_e32 v142, v140
	v_mul_f32_e32 v140, 0xbfb8aa3b, v141
	v_exp_f32_e32 v143, v140
	v_pk_mul_f32 v[140:141], v[114:115], v[214:215] op_sel_hi:[1,0]
	v_exp_f32_e32 v137, v137
	v_mul_f32_e32 v140, 0xbfb8aa3b, v140
	v_exp_f32_e32 v140, v140
	v_mul_f32_e32 v141, 0xbfb8aa3b, v141
	v_exp_f32_e32 v139, v139
	v_exp_f32_e32 v141, v141
	v_add_f32_e32 v140, 1.0, v140
	v_add_f32_e32 v133, 1.0, v133
	v_add_f32_e32 v135, 1.0, v135
	v_add_f32_e32 v137, 1.0, v137
	v_add_f32_e32 v139, 1.0, v139
	v_add_f32_e32 v142, 1.0, v142
	v_add_f32_e32 v143, 1.0, v143
	v_rcp_f32_e32 v145, v140
	v_add_f32_e32 v140, 1.0, v141
	v_rcp_f32_e32 v133, v133
	v_rcp_f32_e32 v135, v135
	v_rcp_f32_e32 v137, v137
	v_rcp_f32_e32 v139, v139
	v_rcp_f32_e32 v142, v142
	v_rcp_f32_e32 v143, v143
	v_rcp_f32_e32 v147, v140
	v_cvt_pk_bf16_f32 v140, v133, v135
	v_cvt_pk_bf16_f32 v141, v137, v139
	v_cvt_pk_bf16_f32 v142, v142, v143
	v_cvt_pk_bf16_f32 v143, v145, v147
	global_store_dwordx4 v[130:131], v[140:143], off offset:256 nt
	v_lshlrev_b64 v[130:131], 11, v[208:209]
	v_lshl_add_u64 v[130:131], v[128:129], 0, v[130:131]
	v_pk_mul_f32 v[140:141], v[108:109], v[212:213] op_sel_hi:[1,0]
	s_nop 0
	v_mul_f32_e32 v133, 0xbfb8aa3b, v140
	v_mul_f32_e32 v135, 0xbfb8aa3b, v141
	v_pk_mul_f32 v[140:141], v[110:111], v[212:213] op_sel_hi:[1,0]
	v_exp_f32_e32 v133, v133
	v_mul_f32_e32 v137, 0xbfb8aa3b, v140
	v_mul_f32_e32 v139, 0xbfb8aa3b, v141
	v_pk_mul_f32 v[140:141], v[100:101], v[212:213] op_sel_hi:[1,0]
	v_exp_f32_e32 v135, v135
	v_mul_f32_e32 v140, 0xbfb8aa3b, v140
	v_exp_f32_e32 v142, v140
	v_mul_f32_e32 v140, 0xbfb8aa3b, v141
	v_exp_f32_e32 v143, v140
	v_pk_mul_f32 v[140:141], v[102:103], v[212:213] op_sel_hi:[1,0]
	v_exp_f32_e32 v137, v137
	v_mul_f32_e32 v140, 0xbfb8aa3b, v140
	v_exp_f32_e32 v140, v140
	v_mul_f32_e32 v141, 0xbfb8aa3b, v141
	v_exp_f32_e32 v139, v139
	v_exp_f32_e32 v141, v141
	v_add_f32_e32 v140, 1.0, v140
	v_add_f32_e32 v133, 1.0, v133
	v_add_f32_e32 v135, 1.0, v135
	v_add_f32_e32 v137, 1.0, v137
	v_add_f32_e32 v139, 1.0, v139
	v_add_f32_e32 v142, 1.0, v142
	v_add_f32_e32 v143, 1.0, v143
	v_rcp_f32_e32 v145, v140
	v_add_f32_e32 v140, 1.0, v141
	v_rcp_f32_e32 v133, v133
	v_rcp_f32_e32 v135, v135
	v_rcp_f32_e32 v137, v137
	v_rcp_f32_e32 v139, v139
	v_rcp_f32_e32 v142, v142
	v_rcp_f32_e32 v143, v143
	v_rcp_f32_e32 v147, v140
	v_cvt_pk_bf16_f32 v140, v133, v135
	v_cvt_pk_bf16_f32 v141, v137, v139
	v_cvt_pk_bf16_f32 v142, v142, v143
	v_cvt_pk_bf16_f32 v143, v145, v147
	global_store_dwordx4 v[130:131], v[140:143], off nt
	s_nop 1
	v_pk_mul_f32 v[140:141], v[104:105], v[212:213] op_sel_hi:[1,0]
	s_nop 0
	v_mul_f32_e32 v133, 0xbfb8aa3b, v140
	v_mul_f32_e32 v135, 0xbfb8aa3b, v141
	v_pk_mul_f32 v[140:141], v[106:107], v[212:213] op_sel_hi:[1,0]
	v_exp_f32_e32 v133, v133
	v_mul_f32_e32 v137, 0xbfb8aa3b, v140
	v_mul_f32_e32 v139, 0xbfb8aa3b, v141
	v_pk_mul_f32 v[140:141], v[96:97], v[212:213] op_sel_hi:[1,0]
	v_exp_f32_e32 v135, v135
	v_mul_f32_e32 v140, 0xbfb8aa3b, v140
	v_exp_f32_e32 v142, v140
	v_mul_f32_e32 v140, 0xbfb8aa3b, v141
	v_exp_f32_e32 v143, v140
	v_pk_mul_f32 v[140:141], v[98:99], v[212:213] op_sel_hi:[1,0]
	v_exp_f32_e32 v137, v137
	v_mul_f32_e32 v140, 0xbfb8aa3b, v140
	v_exp_f32_e32 v140, v140
	v_mul_f32_e32 v141, 0xbfb8aa3b, v141
	v_exp_f32_e32 v139, v139
	v_exp_f32_e32 v141, v141
	v_add_f32_e32 v140, 1.0, v140
	v_add_f32_e32 v133, 1.0, v133
	v_add_f32_e32 v135, 1.0, v135
	v_add_f32_e32 v137, 1.0, v137
	v_add_f32_e32 v139, 1.0, v139
	v_add_f32_e32 v142, 1.0, v142
	v_add_f32_e32 v143, 1.0, v143
	v_rcp_f32_e32 v145, v140
	v_add_f32_e32 v140, 1.0, v141
	v_rcp_f32_e32 v133, v133
	v_rcp_f32_e32 v135, v135
	v_rcp_f32_e32 v137, v137
	v_rcp_f32_e32 v139, v139
	v_rcp_f32_e32 v142, v142
	v_rcp_f32_e32 v143, v143
	v_rcp_f32_e32 v147, v140
	v_cvt_pk_bf16_f32 v140, v133, v135
	v_cvt_pk_bf16_f32 v141, v137, v139
	v_cvt_pk_bf16_f32 v142, v142, v143
	v_cvt_pk_bf16_f32 v143, v145, v147
	global_store_dwordx4 v[130:131], v[140:143], off offset:256 nt
	v_lshlrev_b64 v[130:131], 11, v[206:207]
	v_lshl_add_u64 v[130:131], v[128:129], 0, v[130:131]
	v_pk_mul_f32 v[140:141], v[92:93], v[146:147] op_sel_hi:[1,0]
	s_nop 0
	v_mul_f32_e32 v133, 0xbfb8aa3b, v140
	v_mul_f32_e32 v135, 0xbfb8aa3b, v141
	v_pk_mul_f32 v[140:141], v[94:95], v[146:147] op_sel_hi:[1,0]
	v_exp_f32_e32 v133, v133
	v_mul_f32_e32 v137, 0xbfb8aa3b, v140
	v_mul_f32_e32 v139, 0xbfb8aa3b, v141
	v_pk_mul_f32 v[140:141], v[84:85], v[146:147] op_sel_hi:[1,0]
	v_exp_f32_e32 v135, v135
	v_mul_f32_e32 v140, 0xbfb8aa3b, v140
	v_exp_f32_e32 v142, v140
	v_mul_f32_e32 v140, 0xbfb8aa3b, v141
	v_exp_f32_e32 v143, v140
	v_pk_mul_f32 v[140:141], v[86:87], v[146:147] op_sel_hi:[1,0]
	v_exp_f32_e32 v137, v137
	v_mul_f32_e32 v140, 0xbfb8aa3b, v140
	v_exp_f32_e32 v140, v140
	v_mul_f32_e32 v141, 0xbfb8aa3b, v141
	v_exp_f32_e32 v139, v139
	v_exp_f32_e32 v141, v141
	v_add_f32_e32 v140, 1.0, v140
	v_add_f32_e32 v133, 1.0, v133
	v_add_f32_e32 v135, 1.0, v135
	v_add_f32_e32 v137, 1.0, v137
	v_add_f32_e32 v139, 1.0, v139
	v_add_f32_e32 v142, 1.0, v142
	v_add_f32_e32 v143, 1.0, v143
	v_rcp_f32_e32 v145, v140
	v_add_f32_e32 v140, 1.0, v141
	v_rcp_f32_e32 v133, v133
	v_rcp_f32_e32 v135, v135
	v_rcp_f32_e32 v137, v137
	v_rcp_f32_e32 v139, v139
	v_rcp_f32_e32 v142, v142
	v_rcp_f32_e32 v143, v143
	v_rcp_f32_e32 v147, v140
	v_cvt_pk_bf16_f32 v140, v133, v135
	v_cvt_pk_bf16_f32 v141, v137, v139
	v_cvt_pk_bf16_f32 v142, v142, v143
	v_cvt_pk_bf16_f32 v143, v145, v147
	global_store_dwordx4 v[130:131], v[140:143], off nt
	s_nop 1
	v_pk_mul_f32 v[140:141], v[88:89], v[146:147] op_sel_hi:[1,0]
	s_nop 0
	v_mul_f32_e32 v133, 0xbfb8aa3b, v140
	v_mul_f32_e32 v135, 0xbfb8aa3b, v141
	v_pk_mul_f32 v[140:141], v[90:91], v[146:147] op_sel_hi:[1,0]
	v_exp_f32_e32 v133, v133
	v_mul_f32_e32 v137, 0xbfb8aa3b, v140
	v_mul_f32_e32 v139, 0xbfb8aa3b, v141
	v_pk_mul_f32 v[140:141], v[80:81], v[146:147] op_sel_hi:[1,0]
	v_exp_f32_e32 v135, v135
	v_mul_f32_e32 v140, 0xbfb8aa3b, v140
	v_exp_f32_e32 v142, v140
	v_mul_f32_e32 v140, 0xbfb8aa3b, v141
	v_exp_f32_e32 v143, v140
	v_pk_mul_f32 v[140:141], v[82:83], v[146:147] op_sel_hi:[1,0]
	v_exp_f32_e32 v137, v137
	v_mul_f32_e32 v140, 0xbfb8aa3b, v140
	v_exp_f32_e32 v140, v140
	v_mul_f32_e32 v141, 0xbfb8aa3b, v141
	v_exp_f32_e32 v139, v139
	v_exp_f32_e32 v141, v141
	v_add_f32_e32 v140, 1.0, v140
	v_add_f32_e32 v133, 1.0, v133
	v_add_f32_e32 v135, 1.0, v135
	v_add_f32_e32 v137, 1.0, v137
	v_add_f32_e32 v139, 1.0, v139
	v_add_f32_e32 v142, 1.0, v142
	v_add_f32_e32 v143, 1.0, v143
	v_rcp_f32_e32 v145, v140
	v_add_f32_e32 v140, 1.0, v141
	v_rcp_f32_e32 v133, v133
	v_rcp_f32_e32 v135, v135
	v_rcp_f32_e32 v137, v137
	v_rcp_f32_e32 v139, v139
	v_rcp_f32_e32 v142, v142
	v_rcp_f32_e32 v143, v143
	v_rcp_f32_e32 v147, v140
	v_cvt_pk_bf16_f32 v140, v133, v135
	v_cvt_pk_bf16_f32 v141, v137, v139
	v_cvt_pk_bf16_f32 v142, v142, v143
	v_cvt_pk_bf16_f32 v143, v145, v147
	global_store_dwordx4 v[130:131], v[140:143], off offset:256 nt
	v_lshlrev_b64 v[130:131], 11, v[204:205]
	v_lshl_add_u64 v[130:131], v[128:129], 0, v[130:131]
	v_pk_mul_f32 v[140:141], v[76:77], v[144:145] op_sel_hi:[1,0]
	s_nop 0
	v_mul_f32_e32 v133, 0xbfb8aa3b, v140
	v_mul_f32_e32 v135, 0xbfb8aa3b, v141
	v_pk_mul_f32 v[140:141], v[78:79], v[144:145] op_sel_hi:[1,0]
	v_exp_f32_e32 v133, v133
	v_mul_f32_e32 v137, 0xbfb8aa3b, v140
	v_mul_f32_e32 v139, 0xbfb8aa3b, v141
	v_pk_mul_f32 v[140:141], v[68:69], v[144:145] op_sel_hi:[1,0]
	v_exp_f32_e32 v135, v135
	v_mul_f32_e32 v140, 0xbfb8aa3b, v140
	v_exp_f32_e32 v142, v140
	v_mul_f32_e32 v140, 0xbfb8aa3b, v141
	v_exp_f32_e32 v143, v140
	v_pk_mul_f32 v[140:141], v[70:71], v[144:145] op_sel_hi:[1,0]
	v_exp_f32_e32 v137, v137
	v_mul_f32_e32 v140, 0xbfb8aa3b, v140
	v_exp_f32_e32 v140, v140
	v_mul_f32_e32 v141, 0xbfb8aa3b, v141
	v_exp_f32_e32 v139, v139
	v_exp_f32_e32 v141, v141
	v_add_f32_e32 v140, 1.0, v140
	v_add_f32_e32 v133, 1.0, v133
	v_add_f32_e32 v135, 1.0, v135
	v_add_f32_e32 v137, 1.0, v137
	v_add_f32_e32 v139, 1.0, v139
	v_add_f32_e32 v142, 1.0, v142
	v_add_f32_e32 v143, 1.0, v143
	v_rcp_f32_e32 v145, v140
	v_add_f32_e32 v140, 1.0, v141
	v_rcp_f32_e32 v133, v133
	v_rcp_f32_e32 v135, v135
	v_rcp_f32_e32 v137, v137
	v_rcp_f32_e32 v139, v139
	v_rcp_f32_e32 v142, v142
	v_rcp_f32_e32 v143, v143
	v_rcp_f32_e32 v147, v140
	v_cvt_pk_bf16_f32 v140, v133, v135
	v_cvt_pk_bf16_f32 v141, v137, v139
	v_cvt_pk_bf16_f32 v142, v142, v143
	v_cvt_pk_bf16_f32 v143, v145, v147
	global_store_dwordx4 v[130:131], v[140:143], off nt
	s_nop 1
	v_pk_mul_f32 v[140:141], v[72:73], v[144:145] op_sel_hi:[1,0]
	s_nop 0
	v_mul_f32_e32 v133, 0xbfb8aa3b, v140
	v_mul_f32_e32 v135, 0xbfb8aa3b, v141
	v_pk_mul_f32 v[140:141], v[74:75], v[144:145] op_sel_hi:[1,0]
	v_exp_f32_e32 v133, v133
	v_mul_f32_e32 v137, 0xbfb8aa3b, v140
	v_mul_f32_e32 v139, 0xbfb8aa3b, v141
	v_pk_mul_f32 v[140:141], v[64:65], v[144:145] op_sel_hi:[1,0]
	v_exp_f32_e32 v135, v135
	v_mul_f32_e32 v140, 0xbfb8aa3b, v140
	v_exp_f32_e32 v142, v140
	v_mul_f32_e32 v140, 0xbfb8aa3b, v141
	v_exp_f32_e32 v143, v140
	v_pk_mul_f32 v[140:141], v[66:67], v[144:145] op_sel_hi:[1,0]
	v_exp_f32_e32 v137, v137
	v_mul_f32_e32 v140, 0xbfb8aa3b, v140
	v_exp_f32_e32 v140, v140
	v_mul_f32_e32 v141, 0xbfb8aa3b, v141
	v_exp_f32_e32 v139, v139
	v_exp_f32_e32 v141, v141
	v_add_f32_e32 v140, 1.0, v140
	v_add_f32_e32 v133, 1.0, v133
	v_add_f32_e32 v135, 1.0, v135
	v_add_f32_e32 v137, 1.0, v137
	v_add_f32_e32 v139, 1.0, v139
	v_add_f32_e32 v142, 1.0, v142
	v_add_f32_e32 v143, 1.0, v143
	v_rcp_f32_e32 v145, v140
	v_add_f32_e32 v140, 1.0, v141
	v_rcp_f32_e32 v133, v133
	v_rcp_f32_e32 v135, v135
	v_rcp_f32_e32 v137, v137
	v_rcp_f32_e32 v139, v139
	v_rcp_f32_e32 v142, v142
	v_rcp_f32_e32 v143, v143
	v_rcp_f32_e32 v147, v140
	v_cvt_pk_bf16_f32 v140, v133, v135
	v_cvt_pk_bf16_f32 v141, v137, v139
	v_cvt_pk_bf16_f32 v142, v142, v143
	v_cvt_pk_bf16_f32 v143, v145, v147
	global_store_dwordx4 v[130:131], v[140:143], off offset:256 nt
	v_lshlrev_b64 v[130:131], 11, v[202:203]
	v_lshl_add_u64 v[130:131], v[128:129], 0, v[130:131]
	v_pk_mul_f32 v[140:141], v[60:61], v[138:139] op_sel_hi:[1,0]
	s_nop 0
	v_mul_f32_e32 v133, 0xbfb8aa3b, v140
	v_mul_f32_e32 v135, 0xbfb8aa3b, v141
	v_pk_mul_f32 v[140:141], v[62:63], v[138:139] op_sel_hi:[1,0]
	v_exp_f32_e32 v133, v133
	v_mul_f32_e32 v139, 0xbfb8aa3b, v141
	v_exp_f32_e32 v139, v139
	v_mul_f32_e32 v137, 0xbfb8aa3b, v140
	v_exp_f32_e32 v135, v135
	v_exp_f32_e32 v137, v137
	v_add_f32_e32 v139, 1.0, v139
	v_rcp_f32_e32 v139, v139
	v_add_f32_e32 v133, 1.0, v133
	v_add_f32_e32 v135, 1.0, v135
	v_add_f32_e32 v137, 1.0, v137
	v_pk_mul_f32 v[140:141], v[52:53], v[138:139] op_sel_hi:[1,0]
	v_rcp_f32_e32 v133, v133
	v_mul_f32_e32 v140, 0xbfb8aa3b, v140
	v_exp_f32_e32 v142, v140
	v_mul_f32_e32 v140, 0xbfb8aa3b, v141
	v_exp_f32_e32 v143, v140
	v_pk_mul_f32 v[140:141], v[54:55], v[138:139] op_sel_hi:[1,0]
	v_add_f32_e32 v142, 1.0, v142
	v_mul_f32_e32 v140, 0xbfb8aa3b, v140
	v_exp_f32_e32 v140, v140
	v_mul_f32_e32 v141, 0xbfb8aa3b, v141
	v_exp_f32_e32 v141, v141
	v_add_f32_e32 v143, 1.0, v143
	v_add_f32_e32 v140, 1.0, v140
	v_rcp_f32_e32 v145, v140
	v_add_f32_e32 v140, 1.0, v141
	v_rcp_f32_e32 v135, v135
	v_rcp_f32_e32 v137, v137
	v_rcp_f32_e32 v142, v142
	v_rcp_f32_e32 v143, v143
	v_rcp_f32_e32 v147, v140
	v_cvt_pk_bf16_f32 v140, v133, v135
	v_cvt_pk_bf16_f32 v141, v137, v139
	v_cvt_pk_bf16_f32 v142, v142, v143
	v_cvt_pk_bf16_f32 v143, v145, v147
	global_store_dwordx4 v[130:131], v[140:143], off nt
	s_nop 1
	v_pk_mul_f32 v[140:141], v[56:57], v[138:139] op_sel_hi:[1,0]
	s_nop 0
	v_mul_f32_e32 v133, 0xbfb8aa3b, v140
	v_mul_f32_e32 v135, 0xbfb8aa3b, v141
	v_pk_mul_f32 v[140:141], v[58:59], v[138:139] op_sel_hi:[1,0]
	v_exp_f32_e32 v133, v133
	v_mul_f32_e32 v139, 0xbfb8aa3b, v141
	v_exp_f32_e32 v139, v139
	v_mul_f32_e32 v137, 0xbfb8aa3b, v140
	v_exp_f32_e32 v135, v135
	v_exp_f32_e32 v137, v137
	v_add_f32_e32 v139, 1.0, v139
	v_rcp_f32_e32 v139, v139
	v_add_f32_e32 v133, 1.0, v133
	v_add_f32_e32 v135, 1.0, v135
	v_add_f32_e32 v137, 1.0, v137
	v_pk_mul_f32 v[140:141], v[48:49], v[138:139] op_sel_hi:[1,0]
	v_rcp_f32_e32 v133, v133
	v_mul_f32_e32 v140, 0xbfb8aa3b, v140
	v_exp_f32_e32 v142, v140
	v_mul_f32_e32 v140, 0xbfb8aa3b, v141
	v_exp_f32_e32 v143, v140
	v_pk_mul_f32 v[140:141], v[50:51], v[138:139] op_sel_hi:[1,0]
	v_add_f32_e32 v142, 1.0, v142
	v_mul_f32_e32 v140, 0xbfb8aa3b, v140
	v_exp_f32_e32 v140, v140
	v_mul_f32_e32 v141, 0xbfb8aa3b, v141
	v_exp_f32_e32 v141, v141
	v_add_f32_e32 v143, 1.0, v143
	v_add_f32_e32 v140, 1.0, v140
	v_rcp_f32_e32 v145, v140
	v_add_f32_e32 v140, 1.0, v141
	v_rcp_f32_e32 v135, v135
	v_rcp_f32_e32 v137, v137
	v_rcp_f32_e32 v142, v142
	v_rcp_f32_e32 v143, v143
	v_rcp_f32_e32 v147, v140
	v_cvt_pk_bf16_f32 v140, v133, v135
	v_cvt_pk_bf16_f32 v141, v137, v139
	v_cvt_pk_bf16_f32 v142, v142, v143
	v_cvt_pk_bf16_f32 v143, v145, v147
	global_store_dwordx4 v[130:131], v[140:143], off offset:256 nt
	v_lshlrev_b64 v[130:131], 11, v[200:201]
	v_lshl_add_u64 v[130:131], v[128:129], 0, v[130:131]
	v_pk_mul_f32 v[140:141], v[44:45], v[136:137] op_sel_hi:[1,0]
	s_nop 0
	v_mul_f32_e32 v133, 0xbfb8aa3b, v140
	v_mul_f32_e32 v135, 0xbfb8aa3b, v141
	v_pk_mul_f32 v[140:141], v[46:47], v[136:137] op_sel_hi:[1,0]
	v_exp_f32_e32 v133, v133
	v_mul_f32_e32 v137, 0xbfb8aa3b, v140
	v_exp_f32_e32 v137, v137
	v_mul_f32_e32 v139, 0xbfb8aa3b, v141
	v_exp_f32_e32 v135, v135
	v_exp_f32_e32 v139, v139
	v_add_f32_e32 v137, 1.0, v137
	v_rcp_f32_e32 v137, v137
	v_add_f32_e32 v133, 1.0, v133
	v_add_f32_e32 v135, 1.0, v135
	v_add_f32_e32 v139, 1.0, v139
	v_pk_mul_f32 v[140:141], v[36:37], v[136:137] op_sel_hi:[1,0]
	v_rcp_f32_e32 v133, v133
	v_mul_f32_e32 v140, 0xbfb8aa3b, v140
	v_exp_f32_e32 v142, v140
	v_mul_f32_e32 v140, 0xbfb8aa3b, v141
	v_exp_f32_e32 v143, v140
	v_pk_mul_f32 v[140:141], v[38:39], v[136:137] op_sel_hi:[1,0]
	v_add_f32_e32 v142, 1.0, v142
	v_mul_f32_e32 v140, 0xbfb8aa3b, v140
	v_exp_f32_e32 v140, v140
	v_mul_f32_e32 v141, 0xbfb8aa3b, v141
	v_exp_f32_e32 v141, v141
	v_add_f32_e32 v143, 1.0, v143
	v_add_f32_e32 v140, 1.0, v140
	v_rcp_f32_e32 v145, v140
	v_add_f32_e32 v140, 1.0, v141
	v_rcp_f32_e32 v135, v135
	v_rcp_f32_e32 v139, v139
	v_rcp_f32_e32 v142, v142
	v_rcp_f32_e32 v143, v143
	v_rcp_f32_e32 v147, v140
	v_cvt_pk_bf16_f32 v140, v133, v135
	v_cvt_pk_bf16_f32 v141, v137, v139
	v_cvt_pk_bf16_f32 v142, v142, v143
	v_cvt_pk_bf16_f32 v143, v145, v147
	global_store_dwordx4 v[130:131], v[140:143], off nt
	s_nop 1
	v_pk_mul_f32 v[140:141], v[40:41], v[136:137] op_sel_hi:[1,0]
	s_nop 0
	v_mul_f32_e32 v133, 0xbfb8aa3b, v140
	v_mul_f32_e32 v135, 0xbfb8aa3b, v141
	v_pk_mul_f32 v[140:141], v[42:43], v[136:137] op_sel_hi:[1,0]
	v_exp_f32_e32 v133, v133
	v_mul_f32_e32 v137, 0xbfb8aa3b, v140
	v_exp_f32_e32 v137, v137
	v_mul_f32_e32 v139, 0xbfb8aa3b, v141
	v_exp_f32_e32 v135, v135
	v_exp_f32_e32 v139, v139
	v_add_f32_e32 v137, 1.0, v137
	v_rcp_f32_e32 v137, v137
	v_add_f32_e32 v133, 1.0, v133
	v_add_f32_e32 v135, 1.0, v135
	v_add_f32_e32 v139, 1.0, v139
	v_pk_mul_f32 v[140:141], v[32:33], v[136:137] op_sel_hi:[1,0]
	v_rcp_f32_e32 v133, v133
	v_mul_f32_e32 v140, 0xbfb8aa3b, v140
	v_exp_f32_e32 v142, v140
	v_mul_f32_e32 v140, 0xbfb8aa3b, v141
	v_exp_f32_e32 v143, v140
	v_pk_mul_f32 v[140:141], v[34:35], v[136:137] op_sel_hi:[1,0]
	v_add_f32_e32 v142, 1.0, v142
	v_mul_f32_e32 v140, 0xbfb8aa3b, v140
	v_exp_f32_e32 v140, v140
	v_mul_f32_e32 v141, 0xbfb8aa3b, v141
	v_exp_f32_e32 v141, v141
	v_add_f32_e32 v143, 1.0, v143
	v_add_f32_e32 v140, 1.0, v140
	v_rcp_f32_e32 v145, v140
	v_add_f32_e32 v140, 1.0, v141
	v_rcp_f32_e32 v135, v135
	v_rcp_f32_e32 v139, v139
	v_rcp_f32_e32 v142, v142
	v_rcp_f32_e32 v143, v143
	v_rcp_f32_e32 v147, v140
	v_cvt_pk_bf16_f32 v140, v133, v135
	v_cvt_pk_bf16_f32 v141, v137, v139
	v_cvt_pk_bf16_f32 v142, v142, v143
	v_cvt_pk_bf16_f32 v143, v145, v147
	global_store_dwordx4 v[130:131], v[140:143], off offset:256 nt
	v_lshlrev_b64 v[130:131], 11, v[198:199]
	v_lshl_add_u64 v[130:131], v[128:129], 0, v[130:131]
	v_pk_mul_f32 v[140:141], v[28:29], v[134:135] op_sel_hi:[1,0]
	s_nop 0
	v_mul_f32_e32 v135, 0xbfb8aa3b, v141
	v_exp_f32_e32 v135, v135
	v_mul_f32_e32 v133, 0xbfb8aa3b, v140
	v_exp_f32_e32 v133, v133
	v_pk_mul_f32 v[140:141], v[30:31], v[134:135] op_sel_hi:[1,0]
	v_add_f32_e32 v135, 1.0, v135
	v_rcp_f32_e32 v135, v135
	v_mul_f32_e32 v137, 0xbfb8aa3b, v140
	v_mul_f32_e32 v139, 0xbfb8aa3b, v141
	v_exp_f32_e32 v137, v137
	v_pk_mul_f32 v[140:141], v[20:21], v[134:135] op_sel_hi:[1,0]
	v_exp_f32_e32 v139, v139
	v_mul_f32_e32 v140, 0xbfb8aa3b, v140
	v_exp_f32_e32 v142, v140
	v_mul_f32_e32 v140, 0xbfb8aa3b, v141
	v_exp_f32_e32 v143, v140
	v_pk_mul_f32 v[140:141], v[22:23], v[134:135] op_sel_hi:[1,0]
	v_add_f32_e32 v133, 1.0, v133
	v_mul_f32_e32 v140, 0xbfb8aa3b, v140
	v_exp_f32_e32 v140, v140
	v_mul_f32_e32 v141, 0xbfb8aa3b, v141
	v_exp_f32_e32 v141, v141
	v_add_f32_e32 v137, 1.0, v137
	v_add_f32_e32 v140, 1.0, v140
	v_add_f32_e32 v139, 1.0, v139
	v_add_f32_e32 v142, 1.0, v142
	v_add_f32_e32 v143, 1.0, v143
	v_rcp_f32_e32 v145, v140
	v_add_f32_e32 v140, 1.0, v141
	v_rcp_f32_e32 v133, v133
	v_rcp_f32_e32 v137, v137
	v_rcp_f32_e32 v139, v139
	v_rcp_f32_e32 v142, v142
	v_rcp_f32_e32 v143, v143
	v_rcp_f32_e32 v147, v140
	v_cvt_pk_bf16_f32 v140, v133, v135
	v_cvt_pk_bf16_f32 v141, v137, v139
	v_cvt_pk_bf16_f32 v142, v142, v143
	v_cvt_pk_bf16_f32 v143, v145, v147
	global_store_dwordx4 v[130:131], v[140:143], off nt
	s_nop 1
	v_pk_mul_f32 v[140:141], v[24:25], v[134:135] op_sel_hi:[1,0]
	s_nop 0
	v_mul_f32_e32 v135, 0xbfb8aa3b, v141
	v_exp_f32_e32 v135, v135
	v_mul_f32_e32 v133, 0xbfb8aa3b, v140
	v_exp_f32_e32 v133, v133
	v_pk_mul_f32 v[140:141], v[26:27], v[134:135] op_sel_hi:[1,0]
	v_add_f32_e32 v135, 1.0, v135
	v_rcp_f32_e32 v135, v135
	v_mul_f32_e32 v137, 0xbfb8aa3b, v140
	v_mul_f32_e32 v139, 0xbfb8aa3b, v141
	v_exp_f32_e32 v137, v137
	v_pk_mul_f32 v[140:141], v[16:17], v[134:135] op_sel_hi:[1,0]
	v_exp_f32_e32 v139, v139
	v_mul_f32_e32 v140, 0xbfb8aa3b, v140
	v_exp_f32_e32 v142, v140
	v_mul_f32_e32 v140, 0xbfb8aa3b, v141
	v_exp_f32_e32 v143, v140
	v_pk_mul_f32 v[140:141], v[18:19], v[134:135] op_sel_hi:[1,0]
	v_add_f32_e32 v133, 1.0, v133
	v_mul_f32_e32 v140, 0xbfb8aa3b, v140
	v_exp_f32_e32 v140, v140
	v_mul_f32_e32 v141, 0xbfb8aa3b, v141
	v_exp_f32_e32 v141, v141
	v_add_f32_e32 v137, 1.0, v137
	v_add_f32_e32 v140, 1.0, v140
	v_add_f32_e32 v139, 1.0, v139
	v_add_f32_e32 v142, 1.0, v142
	v_add_f32_e32 v143, 1.0, v143
	v_rcp_f32_e32 v145, v140
	v_add_f32_e32 v140, 1.0, v141
	v_rcp_f32_e32 v133, v133
	v_rcp_f32_e32 v137, v137
	v_rcp_f32_e32 v139, v139
	v_rcp_f32_e32 v142, v142
	v_rcp_f32_e32 v143, v143
	v_rcp_f32_e32 v147, v140
	v_cvt_pk_bf16_f32 v140, v133, v135
	v_cvt_pk_bf16_f32 v141, v137, v139
	v_cvt_pk_bf16_f32 v142, v142, v143
	v_cvt_pk_bf16_f32 v143, v145, v147
	global_store_dwordx4 v[130:131], v[140:143], off offset:256 nt
	v_lshlrev_b64 v[130:131], 11, v[196:197]
	s_nop 0
	v_lshl_add_u64 v[140:141], v[128:129], 0, v[130:131]
	v_pk_mul_f32 v[128:129], v[12:13], v[132:133] op_sel_hi:[1,0]
	s_nop 0
	v_mul_f32_e32 v128, 0xbfb8aa3b, v128
	v_exp_f32_e32 v130, v128
	v_mul_f32_e32 v128, 0xbfb8aa3b, v129
	v_exp_f32_e32 v131, v128
	v_pk_mul_f32 v[128:129], v[14:15], v[132:133] op_sel_hi:[1,0]
	v_add_f32_e32 v130, 1.0, v130
	v_mul_f32_e32 v128, 0xbfb8aa3b, v128
	v_exp_f32_e32 v128, v128
	v_mul_f32_e32 v129, 0xbfb8aa3b, v129
	v_exp_f32_e32 v129, v129
	v_add_f32_e32 v131, 1.0, v131
	v_add_f32_e32 v128, 1.0, v128
	v_rcp_f32_e32 v133, v128
	v_add_f32_e32 v128, 1.0, v129
	v_rcp_f32_e32 v135, v128
	v_rcp_f32_e32 v130, v130
	v_pk_mul_f32 v[128:129], v[4:5], v[132:133] op_sel_hi:[1,0]
	v_rcp_f32_e32 v131, v131
	v_mul_f32_e32 v128, 0xbfb8aa3b, v128
	v_exp_f32_e32 v137, v128
	v_mul_f32_e32 v128, 0xbfb8aa3b, v129
	v_exp_f32_e32 v139, v128
	v_pk_mul_f32 v[128:129], v[6:7], v[132:133] op_sel_hi:[1,0]
	v_add_f32_e32 v137, 1.0, v137
	v_mul_f32_e32 v128, 0xbfb8aa3b, v128
	v_exp_f32_e32 v128, v128
	v_mul_f32_e32 v129, 0xbfb8aa3b, v129
	v_exp_f32_e32 v129, v129
	v_add_f32_e32 v139, 1.0, v139
	v_add_f32_e32 v128, 1.0, v128
	v_rcp_f32_e32 v142, v128
	v_add_f32_e32 v128, 1.0, v129
	v_rcp_f32_e32 v137, v137
	v_rcp_f32_e32 v139, v139
	v_rcp_f32_e32 v143, v128
	v_cvt_pk_bf16_f32 v128, v130, v131
	v_cvt_pk_bf16_f32 v129, v133, v135
	v_cvt_pk_bf16_f32 v130, v137, v139
	v_cvt_pk_bf16_f32 v131, v142, v143
	global_store_dwordx4 v[140:141], v[128:131], off nt
	s_nop 1
	v_pk_mul_f32 v[128:129], v[8:9], v[132:133] op_sel_hi:[1,0]
	s_nop 0
	v_mul_f32_e32 v128, 0xbfb8aa3b, v128
	v_exp_f32_e32 v130, v128
	v_mul_f32_e32 v128, 0xbfb8aa3b, v129
	v_exp_f32_e32 v131, v128
	v_pk_mul_f32 v[128:129], v[10:11], v[132:133] op_sel_hi:[1,0]
	v_add_f32_e32 v130, 1.0, v130
	v_mul_f32_e32 v128, 0xbfb8aa3b, v128
	v_exp_f32_e32 v128, v128
	v_mul_f32_e32 v129, 0xbfb8aa3b, v129
	v_exp_f32_e32 v129, v129
	v_add_f32_e32 v131, 1.0, v131
	v_add_f32_e32 v128, 1.0, v128
	v_rcp_f32_e32 v133, v128
	v_add_f32_e32 v128, 1.0, v129
	v_rcp_f32_e32 v135, v128
	v_rcp_f32_e32 v130, v130
	v_pk_mul_f32 v[128:129], v[0:1], v[132:133] op_sel_hi:[1,0]
	v_rcp_f32_e32 v131, v131
	v_mul_f32_e32 v128, 0xbfb8aa3b, v128
	v_exp_f32_e32 v137, v128
	v_mul_f32_e32 v128, 0xbfb8aa3b, v129
	v_exp_f32_e32 v139, v128
	v_pk_mul_f32 v[128:129], v[2:3], v[132:133] op_sel_hi:[1,0]
	v_add_f32_e32 v137, 1.0, v137
	v_mul_f32_e32 v128, 0xbfb8aa3b, v128
	v_exp_f32_e32 v128, v128
	v_mul_f32_e32 v129, 0xbfb8aa3b, v129
	v_exp_f32_e32 v129, v129
	v_add_f32_e32 v139, 1.0, v139
	v_add_f32_e32 v128, 1.0, v128
	v_rcp_f32_e32 v142, v128
	v_add_f32_e32 v128, 1.0, v129
	v_rcp_f32_e32 v137, v137
	v_rcp_f32_e32 v139, v139
	v_rcp_f32_e32 v143, v128
	v_cvt_pk_bf16_f32 v128, v130, v131
	v_cvt_pk_bf16_f32 v129, v133, v135
	v_cvt_pk_bf16_f32 v130, v137, v139
	v_cvt_pk_bf16_f32 v131, v142, v143
	global_store_dwordx4 v[140:141], v[128:131], off offset:256 nt
